# full barriers: each XCD's first arriver starts an un-waited L2 write-back so the leader's release has less to drain
# speedup vs baseline: 1.0012x; 1.0012x over previous
; __device__ __forceinline__ unsigned xb_ld(unsigned* p)              { return __hip_atomic_load(p, __ATOMIC_RELAXED, __HIP_MEMORY_SCOPE_AGENT); }
; __device__ __forceinline__ unsigned xb_add(unsigned* p, unsigned v) { return __hip_atomic_fetch_add(p, v, __ATOMIC_RELAXED, __HIP_MEMORY_SCOPE_AGENT); }
; #define XB_SPIN(cond, bar) do { unsigned _sp = 0; while (cond) { __builtin_amdgcn_s_sleep(1); \
;     if ((++_sp & 255u) == 0u) { if (xb_ld(&(bar)[XB_TMO])) break; if (_sp > XB_SPIN_CAP) { atomicAdd(&(bar)[XB_TMO], 1u); break; } } } } while (0)
; __device__ __forceinline__ void xcd_barrier(const XcdBarrier& b) {
;     ...
;         const unsigned old = xb_add(&bar[XB_XSUB(b.x)], 1u);
;         const unsigned gen = old / nloc;
;         if (old + 1u == (gen + 1u) * nloc) {
;             __builtin_amdgcn_fence(__ATOMIC_RELEASE, "agent");
;             asm volatile("s_waitcnt vmcnt(0)" ::: "memory");
;             const unsigned og = xb_add(&bar[XB_TOP], 1u);
;             const unsigned tg = og / nx;
;             if (og + 1u == (tg + 1u) * nx) xb_add(&bar[XB_TOPGEN], 1u);
;             else XB_SPIN(xb_ld(&bar[XB_TOPGEN]) == tg, bar);
.LBB0_1387:
	s_or_b64 exec, exec, s[12:13]
	v_cvt_f32_u32_e32 v4, v2
	s_waitcnt vmcnt(0)
	v_readfirstlane_b32 s3, v3
	v_sub_u32_e32 v3, 0, v2
	v_rcp_iflag_f32_e32 v4, v4
	v_add_u32_e32 v5, s3, v1
	v_mul_f32_e32 v4, 0x4f7ffffe, v4
	v_cvt_u32_f32_e32 v4, v4
	v_mul_lo_u32 v1, v3, v4
	v_mul_hi_u32 v1, v4, v1
	v_add_u32_e32 v1, v4, v1
	v_mul_hi_u32 v1, v5, v1
	v_mul_lo_u32 v3, v1, v2
	v_sub_u32_e32 v3, v5, v3
	v_add_u32_e32 v4, 1, v1
	v_cmp_ge_u32_e32 vcc, v3, v2
	s_nop 1
	v_cndmask_b32_e32 v1, v1, v4, vcc
	v_sub_u32_e32 v4, v3, v2
	v_cndmask_b32_e32 v3, v3, v4, vcc
	v_add_u32_e32 v4, 1, v1
	v_cmp_ge_u32_e32 vcc, v3, v2
	v_add_u32_e32 v3, 1, v5
	s_nop 0
	v_cndmask_b32_e32 v1, v1, v4, vcc
	v_mul_lo_u32 v4, v2, v1
	v_add_u32_e32 v2, v4, v2
	v_cmp_ne_u32_e32 vcc, v3, v2
	s_and_saveexec_b64 s[10:11], vcc
	s_xor_b64 s[10:11], exec, s[10:11]
	s_cbranch_execz .LBB0_1401
	s_waitcnt lgkmcnt(0)
	v_add_u32_e32 v6, 1, v4
	v_cmp_eq_u32_e32 vcc, v3, v6
	s_cbranch_vccz .Lfirstwb_1
	buffer_wbl2 sc1
.Lfirstwb_1:
	buffer_inv sc1
	v_mov_b32_e32 v0, 0x2000
	global_load_dword v0, v0, s[8:9] offset:1024 sc1
	s_add_u32 s16, s8, 0x2400
	s_addc_u32 s17, s9, 0
	s_waitcnt vmcnt(0)
	v_cmp_eq_u32_e32 vcc, v0, v1
	s_and_saveexec_b64 s[12:13], vcc
	s_cbranch_execz .LBB0_1400
	s_add_u32 s14, s54, 0x3085e00
	s_addc_u32 s15, s55, 0
	s_mov_b32 s3, 1
	s_mov_b64 s[18:19], 0
	v_mov_b32_e32 v0, 0
	s_branch .LBB0_1391
